# baseline (speedup 1.0000x reference)
; DI unsigned cvtpk(float lo, float hi) { unsigned r; asm volatile("v_cvt_pk_bf16_f32 %0, %1, %2" : "=v"(r) : "v"(lo), "v"(hi)); return r; }
; DI int crow(int r, int hi) { return (r & 3) + 8 * (r >> 2) + 4 * hi; }
; DI float shx1(float v) { return __int_as_float(__builtin_amdgcn_mov_dpp(__float_as_int(v), 0xB1, 0xf, 0xf, true)); }
; DI int block(const PP& p, const ARef& cur, volatile int* slot, unsigned* ctr, int base, int total, char* lds, Seam& S, bool dummy, const unsigned* nrm) {
;     ...
;     if (hi == 0) li_l[r32] = l_reg; asm volatile("s_waitcnt lgkmcnt(0)" ::: "memory");
;     float rli[16];
; #pragma unroll
;     for (int r = 0; r < 16; ++r) rli[r] = __builtin_amdgcn_rcpf(li_l[crow(r, hi)]);
;     bf16_t* Ow = cur.O + (size_t)(wid * QBLK) * cur.ldo;
; #pragma unroll
;     for (int r = 0; r < 16; ++r) { const int orow = crow(r, hi);
; #pragma unroll
;         for (int d0 = 0; d0 < 4; ++d0) { const float v = o[d0][r] * rli[r];
;             const float vn = shx1(v);
;             if ((r32 & 1) == 0) *(unsigned*)(Ow + (size_t)orow * cur.ldo + d0 * 32 + r32) = cvtpk(v, vn); } }
.Lfa_epi_plain:
	v_cmp_gt_u32_e32 vcc, 32, v221
	s_and_saveexec_b64 s[0:1], vcc
	ds_write_b32 v226, v0
	s_or_b64 exec, exec, s[0:1]
	s_waitcnt lgkmcnt(0)
	ds_read_b128 v[78:81], v225
	ds_read_b128 v[74:77], v225 offset:32
	ds_read_b128 v[70:73], v225 offset:64
	ds_read_b128 v[66:69], v225 offset:96
	s_mul_i32 s4, s67, 0x5800
	s_add_u32 s0, s2, s4
	s_addc_u32 s1, s3, 0
	s_lshl_b32 s5, s64, 12
	s_add_i32 s5, s5, 0x11000
	v_lshlrev_b32_e32 v200, 8, v218
	v_lshl_add_u32 v200, v223, 1, v200
	v_add_u32_e32 v200, s5, v200
	v_lshrrev_b32_e32 v201, 4, v220
	v_and_b32_e32 v202, 15, v220
	v_mul_u32_u24_e64 v203, v201, s35
	v_lshlrev_b32_e32 v201, 8, v201
	v_lshl_add_u32 v201, v202, 4, v201
	v_lshl_add_u32 v203, v202, 4, v203
	v_add_u32_e32 v201, s5, v201
	v_and_b32_e32 v205, 1, v220
	s_waitcnt lgkmcnt(0)
	v_rcp_f32_e32 v78, v78
	v_rcp_f32_e32 v79, v79
	v_rcp_f32_e32 v80, v80
	v_rcp_f32_e32 v81, v81
	v_rcp_f32_e32 v74, v74
	v_rcp_f32_e32 v75, v75
	v_rcp_f32_e32 v76, v76
	v_rcp_f32_e32 v77, v77
	v_rcp_f32_e32 v70, v70
	v_rcp_f32_e32 v71, v71
	v_rcp_f32_e32 v72, v72
	v_rcp_f32_e32 v73, v73
	v_rcp_f32_e32 v66, v66
	v_rcp_f32_e32 v67, v67
	v_rcp_f32_e32 v68, v68
	v_rcp_f32_e32 v69, v69
	v_mul_f32_e32 v82, v50, v78
	v_mul_f32_e32 v83, v34, v78
	v_mul_f32_e32 v84, v18, v78
	v_mul_f32_e32 v85, v2, v78
	v_mul_f32_e32 v86, v51, v79
	v_mul_f32_e32 v87, v35, v79
	v_mul_f32_e32 v88, v19, v79
	v_mul_f32_e32 v89, v3, v79
	v_mul_f32_e32 v90, v52, v80
	v_mul_f32_e32 v91, v36, v80
	v_mul_f32_e32 v92, v20, v80
	v_mul_f32_e32 v93, v4, v80
	v_mul_f32_e32 v94, v53, v81
	v_mul_f32_e32 v95, v37, v81
	v_mul_f32_e32 v96, v21, v81
	v_mul_f32_e32 v97, v5, v81
	v_mul_f32_e32 v106, v54, v74
	v_mul_f32_e32 v107, v38, v74
	v_mul_f32_e32 v108, v22, v74
	v_mul_f32_e32 v109, v6, v74
	v_mul_f32_e32 v110, v55, v75
	v_mul_f32_e32 v111, v39, v75
	v_mul_f32_e32 v112, v23, v75
	v_mul_f32_e32 v113, v7, v75
	v_mul_f32_e32 v114, v56, v76
	v_mul_f32_e32 v115, v40, v76
	v_mul_f32_e32 v116, v24, v76
	v_mul_f32_e32 v117, v8, v76
	v_mul_f32_e32 v118, v57, v77
	v_mul_f32_e32 v119, v41, v77
	v_mul_f32_e32 v120, v25, v77
	v_mul_f32_e32 v121, v9, v77
	v_mov_b32_dpp v163, v82 quad_perm:[1,0,3,2] row_mask:0xf bank_mask:0xf bound_ctrl:1
	v_mov_b32_dpp v164, v83 quad_perm:[1,0,3,2] row_mask:0xf bank_mask:0xf bound_ctrl:1
	v_mov_b32_dpp v165, v84 quad_perm:[1,0,3,2] row_mask:0xf bank_mask:0xf bound_ctrl:1
	v_mov_b32_dpp v166, v85 quad_perm:[1,0,3,2] row_mask:0xf bank_mask:0xf bound_ctrl:1
	v_mov_b32_dpp v167, v86 quad_perm:[1,0,3,2] row_mask:0xf bank_mask:0xf bound_ctrl:1
	v_mov_b32_dpp v168, v87 quad_perm:[1,0,3,2] row_mask:0xf bank_mask:0xf bound_ctrl:1
	v_mov_b32_dpp v169, v88 quad_perm:[1,0,3,2] row_mask:0xf bank_mask:0xf bound_ctrl:1
	v_mov_b32_dpp v170, v89 quad_perm:[1,0,3,2] row_mask:0xf bank_mask:0xf bound_ctrl:1
	v_mov_b32_dpp v171, v90 quad_perm:[1,0,3,2] row_mask:0xf bank_mask:0xf bound_ctrl:1
	v_mov_b32_dpp v172, v91 quad_perm:[1,0,3,2] row_mask:0xf bank_mask:0xf bound_ctrl:1
	v_mov_b32_dpp v173, v92 quad_perm:[1,0,3,2] row_mask:0xf bank_mask:0xf bound_ctrl:1
	v_mov_b32_dpp v174, v93 quad_perm:[1,0,3,2] row_mask:0xf bank_mask:0xf bound_ctrl:1
	v_mov_b32_dpp v175, v94 quad_perm:[1,0,3,2] row_mask:0xf bank_mask:0xf bound_ctrl:1
	v_mov_b32_dpp v176, v95 quad_perm:[1,0,3,2] row_mask:0xf bank_mask:0xf bound_ctrl:1
	v_mov_b32_dpp v177, v96 quad_perm:[1,0,3,2] row_mask:0xf bank_mask:0xf bound_ctrl:1
	v_mov_b32_dpp v178, v97 quad_perm:[1,0,3,2] row_mask:0xf bank_mask:0xf bound_ctrl:1
	v_mov_b32_dpp v179, v106 quad_perm:[1,0,3,2] row_mask:0xf bank_mask:0xf bound_ctrl:1
	v_mov_b32_dpp v180, v107 quad_perm:[1,0,3,2] row_mask:0xf bank_mask:0xf bound_ctrl:1
	v_mov_b32_dpp v181, v108 quad_perm:[1,0,3,2] row_mask:0xf bank_mask:0xf bound_ctrl:1
	v_mov_b32_dpp v182, v109 quad_perm:[1,0,3,2] row_mask:0xf bank_mask:0xf bound_ctrl:1
	v_mov_b32_dpp v183, v110 quad_perm:[1,0,3,2] row_mask:0xf bank_mask:0xf bound_ctrl:1
	v_mov_b32_dpp v184, v111 quad_perm:[1,0,3,2] row_mask:0xf bank_mask:0xf bound_ctrl:1
	v_mov_b32_dpp v185, v112 quad_perm:[1,0,3,2] row_mask:0xf bank_mask:0xf bound_ctrl:1
	v_mov_b32_dpp v186, v113 quad_perm:[1,0,3,2] row_mask:0xf bank_mask:0xf bound_ctrl:1
	v_mov_b32_dpp v187, v114 quad_perm:[1,0,3,2] row_mask:0xf bank_mask:0xf bound_ctrl:1
	v_mov_b32_dpp v188, v115 quad_perm:[1,0,3,2] row_mask:0xf bank_mask:0xf bound_ctrl:1
	v_mov_b32_dpp v189, v116 quad_perm:[1,0,3,2] row_mask:0xf bank_mask:0xf bound_ctrl:1
	v_mov_b32_dpp v190, v117 quad_perm:[1,0,3,2] row_mask:0xf bank_mask:0xf bound_ctrl:1
	v_mov_b32_dpp v191, v118 quad_perm:[1,0,3,2] row_mask:0xf bank_mask:0xf bound_ctrl:1
	v_mov_b32_dpp v192, v119 quad_perm:[1,0,3,2] row_mask:0xf bank_mask:0xf bound_ctrl:1
	v_mov_b32_dpp v193, v120 quad_perm:[1,0,3,2] row_mask:0xf bank_mask:0xf bound_ctrl:1
	v_mov_b32_dpp v194, v121 quad_perm:[1,0,3,2] row_mask:0xf bank_mask:0xf bound_ctrl:1
	v_cvt_pk_bf16_f32 v82, v82, v163
	v_cvt_pk_bf16_f32 v83, v83, v164
	v_cvt_pk_bf16_f32 v84, v84, v165
	v_cvt_pk_bf16_f32 v85, v85, v166
	v_cvt_pk_bf16_f32 v86, v86, v167
	v_cvt_pk_bf16_f32 v87, v87, v168
	v_cvt_pk_bf16_f32 v88, v88, v169
	v_cvt_pk_bf16_f32 v89, v89, v170
	v_cvt_pk_bf16_f32 v90, v90, v171
	v_cvt_pk_bf16_f32 v91, v91, v172
	v_cvt_pk_bf16_f32 v92, v92, v173
	v_cvt_pk_bf16_f32 v93, v93, v174
	v_cvt_pk_bf16_f32 v94, v94, v175
	v_cvt_pk_bf16_f32 v95, v95, v176
	v_cvt_pk_bf16_f32 v96, v96, v177
	v_cvt_pk_bf16_f32 v97, v97, v178
	v_cvt_pk_bf16_f32 v106, v106, v179
	v_cvt_pk_bf16_f32 v107, v107, v180
	v_cvt_pk_bf16_f32 v108, v108, v181
	v_cvt_pk_bf16_f32 v109, v109, v182
	v_cvt_pk_bf16_f32 v110, v110, v183
	v_cvt_pk_bf16_f32 v111, v111, v184
	v_cvt_pk_bf16_f32 v112, v112, v185
; DI unsigned cvtpk(float lo, float hi) { unsigned r; asm volatile("v_cvt_pk_bf16_f32 %0, %1, %2" : "=v"(r) : "v"(lo), "v"(hi)); return r; }
; DI float shx1(float v) { return __int_as_float(__builtin_amdgcn_mov_dpp(__float_as_int(v), 0xB1, 0xf, 0xf, true)); }
; DI int block(const PP& p, const ARef& cur, volatile int* slot, unsigned* ctr, int base, int total, char* lds, Seam& S, bool dummy, const unsigned* nrm) {
;     ...
;         for (int d0 = 0; d0 < 4; ++d0) { const float v = o[d0][r] * rli[r];
;             const float vn = shx1(v);
;             if ((r32 & 1) == 0) *(unsigned*)(Ow + (size_t)orow * cur.ldo + d0 * 32 + r32) = cvtpk(v, vn); } }
	v_cvt_pk_bf16_f32 v113, v113, v186
	v_cvt_pk_bf16_f32 v114, v114, v187
	v_cvt_pk_bf16_f32 v115, v115, v188
	v_cvt_pk_bf16_f32 v116, v116, v189
	v_cvt_pk_bf16_f32 v117, v117, v190
	v_cvt_pk_bf16_f32 v118, v118, v191
	v_cvt_pk_bf16_f32 v119, v119, v192
	v_cvt_pk_bf16_f32 v120, v120, v193
	v_cvt_pk_bf16_f32 v121, v121, v194
	v_cmp_eq_u32_e32 vcc, 0, v205
	s_and_saveexec_b64 s[12:13], vcc
	ds_write_b32 v200, v82 offset:0
	ds_write_b32 v200, v83 offset:64
	ds_write_b32 v200, v84 offset:128
	ds_write_b32 v200, v85 offset:192
	ds_write_b32 v200, v86 offset:256
	ds_write_b32 v200, v87 offset:320
	ds_write_b32 v200, v88 offset:384
	ds_write_b32 v200, v89 offset:448
	ds_write_b32 v200, v90 offset:512
	ds_write_b32 v200, v91 offset:576
	ds_write_b32 v200, v92 offset:640
	ds_write_b32 v200, v93 offset:704
	ds_write_b32 v200, v94 offset:768
	ds_write_b32 v200, v95 offset:832
	ds_write_b32 v200, v96 offset:896
	ds_write_b32 v200, v97 offset:960
	ds_write_b32 v200, v106 offset:2048
	ds_write_b32 v200, v107 offset:2112
	ds_write_b32 v200, v108 offset:2176
	ds_write_b32 v200, v109 offset:2240
	ds_write_b32 v200, v110 offset:2304
	ds_write_b32 v200, v111 offset:2368
	ds_write_b32 v200, v112 offset:2432
	ds_write_b32 v200, v113 offset:2496
	ds_write_b32 v200, v114 offset:2560
	ds_write_b32 v200, v115 offset:2624
	ds_write_b32 v200, v116 offset:2688
	ds_write_b32 v200, v117 offset:2752
	ds_write_b32 v200, v118 offset:2816
	ds_write_b32 v200, v119 offset:2880
	ds_write_b32 v200, v120 offset:2944
	ds_write_b32 v200, v121 offset:3008
	s_or_b64 exec, exec, s[12:13]
	s_waitcnt lgkmcnt(0)
	ds_read_b128 v[122:125], v201 offset:0
	ds_read_b128 v[126:129], v201 offset:1024
	ds_read_b128 v[164:167], v201 offset:2048
	ds_read_b128 v[168:171], v201 offset:3072
	s_waitcnt lgkmcnt(0)
; DI unsigned cvtpk(float lo, float hi) { unsigned r; asm volatile("v_cvt_pk_bf16_f32 %0, %1, %2" : "=v"(r) : "v"(lo), "v"(hi)); return r; }
; DI int crow(int r, int hi) { return (r & 3) + 8 * (r >> 2) + 4 * hi; }
; DI float shx1(float v) { return __int_as_float(__builtin_amdgcn_mov_dpp(__float_as_int(v), 0xB1, 0xf, 0xf, true)); }
; DI int block(const PP& p, const ARef& cur, volatile int* slot, unsigned* ctr, int base, int total, char* lds, Seam& S, bool dummy, const unsigned* nrm) {
;     ...
;     bf16_t* Ow = cur.O + (size_t)(wid * QBLK) * cur.ldo;
; #pragma unroll
;     for (int r = 0; r < 16; ++r) { const int orow = crow(r, hi);
; #pragma unroll
;         for (int d0 = 0; d0 < 4; ++d0) { const float v = o[d0][r] * rli[r];
;             const float vn = shx1(v);
;             if ((r32 & 1) == 0) *(unsigned*)(Ow + (size_t)orow * cur.ldo + d0 * 32 + r32) = cvtpk(v, vn); } }
	v_add_u32_e32 v204, 0x0, v203
	global_store_dwordx4 v204, v[122:125], s[0:1]
	v_add_u32_e32 v204, 0x16000, v203
	global_store_dwordx4 v204, v[126:129], s[0:1]
	v_add_u32_e32 v204, 0x2c000, v203
	global_store_dwordx4 v204, v[164:167], s[0:1]
	v_add_u32_e32 v204, 0x42000, v203
	global_store_dwordx4 v204, v[168:171], s[0:1]
	v_mul_f32_e32 v82, v58, v70
	v_mul_f32_e32 v83, v42, v70
	v_mul_f32_e32 v84, v26, v70
	v_mul_f32_e32 v85, v10, v70
	v_mul_f32_e32 v86, v59, v71
	v_mul_f32_e32 v87, v43, v71
	v_mul_f32_e32 v88, v27, v71
	v_mul_f32_e32 v89, v11, v71
	v_mul_f32_e32 v90, v60, v72
	v_mul_f32_e32 v91, v44, v72
	v_mul_f32_e32 v92, v28, v72
	v_mul_f32_e32 v93, v12, v72
	v_mul_f32_e32 v94, v61, v73
	v_mul_f32_e32 v95, v45, v73
	v_mul_f32_e32 v96, v29, v73
	v_mul_f32_e32 v97, v13, v73
	v_mul_f32_e32 v106, v62, v66
	v_mul_f32_e32 v107, v46, v66
	v_mul_f32_e32 v108, v30, v66
	v_mul_f32_e32 v109, v14, v66
	v_mul_f32_e32 v110, v63, v67
	v_mul_f32_e32 v111, v47, v67
	v_mul_f32_e32 v112, v31, v67
	v_mul_f32_e32 v113, v15, v67
	v_mul_f32_e32 v114, v64, v68
	v_mul_f32_e32 v115, v48, v68
	v_mul_f32_e32 v116, v32, v68
	v_mul_f32_e32 v117, v16, v68
	v_mul_f32_e32 v118, v65, v69
	v_mul_f32_e32 v119, v49, v69
	v_mul_f32_e32 v120, v33, v69
	v_mul_f32_e32 v121, v17, v69
	v_mov_b32_dpp v163, v82 quad_perm:[1,0,3,2] row_mask:0xf bank_mask:0xf bound_ctrl:1
	v_mov_b32_dpp v164, v83 quad_perm:[1,0,3,2] row_mask:0xf bank_mask:0xf bound_ctrl:1
	v_mov_b32_dpp v165, v84 quad_perm:[1,0,3,2] row_mask:0xf bank_mask:0xf bound_ctrl:1
	v_mov_b32_dpp v166, v85 quad_perm:[1,0,3,2] row_mask:0xf bank_mask:0xf bound_ctrl:1
	v_mov_b32_dpp v167, v86 quad_perm:[1,0,3,2] row_mask:0xf bank_mask:0xf bound_ctrl:1
	v_mov_b32_dpp v168, v87 quad_perm:[1,0,3,2] row_mask:0xf bank_mask:0xf bound_ctrl:1
	v_mov_b32_dpp v169, v88 quad_perm:[1,0,3,2] row_mask:0xf bank_mask:0xf bound_ctrl:1
	v_mov_b32_dpp v170, v89 quad_perm:[1,0,3,2] row_mask:0xf bank_mask:0xf bound_ctrl:1
	v_mov_b32_dpp v171, v90 quad_perm:[1,0,3,2] row_mask:0xf bank_mask:0xf bound_ctrl:1
	v_mov_b32_dpp v172, v91 quad_perm:[1,0,3,2] row_mask:0xf bank_mask:0xf bound_ctrl:1
	v_mov_b32_dpp v173, v92 quad_perm:[1,0,3,2] row_mask:0xf bank_mask:0xf bound_ctrl:1
	v_mov_b32_dpp v174, v93 quad_perm:[1,0,3,2] row_mask:0xf bank_mask:0xf bound_ctrl:1
	v_mov_b32_dpp v175, v94 quad_perm:[1,0,3,2] row_mask:0xf bank_mask:0xf bound_ctrl:1
	v_mov_b32_dpp v176, v95 quad_perm:[1,0,3,2] row_mask:0xf bank_mask:0xf bound_ctrl:1
	v_mov_b32_dpp v177, v96 quad_perm:[1,0,3,2] row_mask:0xf bank_mask:0xf bound_ctrl:1
	v_mov_b32_dpp v178, v97 quad_perm:[1,0,3,2] row_mask:0xf bank_mask:0xf bound_ctrl:1
	v_mov_b32_dpp v179, v106 quad_perm:[1,0,3,2] row_mask:0xf bank_mask:0xf bound_ctrl:1
	v_mov_b32_dpp v180, v107 quad_perm:[1,0,3,2] row_mask:0xf bank_mask:0xf bound_ctrl:1
	v_mov_b32_dpp v181, v108 quad_perm:[1,0,3,2] row_mask:0xf bank_mask:0xf bound_ctrl:1
	v_mov_b32_dpp v182, v109 quad_perm:[1,0,3,2] row_mask:0xf bank_mask:0xf bound_ctrl:1
	v_mov_b32_dpp v183, v110 quad_perm:[1,0,3,2] row_mask:0xf bank_mask:0xf bound_ctrl:1
	v_mov_b32_dpp v184, v111 quad_perm:[1,0,3,2] row_mask:0xf bank_mask:0xf bound_ctrl:1
	v_mov_b32_dpp v185, v112 quad_perm:[1,0,3,2] row_mask:0xf bank_mask:0xf bound_ctrl:1
	v_mov_b32_dpp v186, v113 quad_perm:[1,0,3,2] row_mask:0xf bank_mask:0xf bound_ctrl:1
	v_mov_b32_dpp v187, v114 quad_perm:[1,0,3,2] row_mask:0xf bank_mask:0xf bound_ctrl:1
	v_mov_b32_dpp v188, v115 quad_perm:[1,0,3,2] row_mask:0xf bank_mask:0xf bound_ctrl:1
	v_mov_b32_dpp v189, v116 quad_perm:[1,0,3,2] row_mask:0xf bank_mask:0xf bound_ctrl:1
	v_mov_b32_dpp v190, v117 quad_perm:[1,0,3,2] row_mask:0xf bank_mask:0xf bound_ctrl:1
	v_mov_b32_dpp v191, v118 quad_perm:[1,0,3,2] row_mask:0xf bank_mask:0xf bound_ctrl:1
	v_mov_b32_dpp v192, v119 quad_perm:[1,0,3,2] row_mask:0xf bank_mask:0xf bound_ctrl:1
	v_mov_b32_dpp v193, v120 quad_perm:[1,0,3,2] row_mask:0xf bank_mask:0xf bound_ctrl:1
	v_mov_b32_dpp v194, v121 quad_perm:[1,0,3,2] row_mask:0xf bank_mask:0xf bound_ctrl:1
	v_cvt_pk_bf16_f32 v82, v82, v163
	v_cvt_pk_bf16_f32 v83, v83, v164
	v_cvt_pk_bf16_f32 v84, v84, v165
	v_cvt_pk_bf16_f32 v85, v85, v166
	v_cvt_pk_bf16_f32 v86, v86, v167
	v_cvt_pk_bf16_f32 v87, v87, v168
	v_cvt_pk_bf16_f32 v88, v88, v169
	v_cvt_pk_bf16_f32 v89, v89, v170
	v_cvt_pk_bf16_f32 v90, v90, v171
	v_cvt_pk_bf16_f32 v91, v91, v172
	v_cvt_pk_bf16_f32 v92, v92, v173
	v_cvt_pk_bf16_f32 v93, v93, v174
	v_cvt_pk_bf16_f32 v94, v94, v175
	v_cvt_pk_bf16_f32 v95, v95, v176
	v_cvt_pk_bf16_f32 v96, v96, v177
	v_cvt_pk_bf16_f32 v97, v97, v178
	v_cvt_pk_bf16_f32 v106, v106, v179
	v_cvt_pk_bf16_f32 v107, v107, v180
	v_cvt_pk_bf16_f32 v108, v108, v181
	v_cvt_pk_bf16_f32 v109, v109, v182
	v_cvt_pk_bf16_f32 v110, v110, v183
	v_cvt_pk_bf16_f32 v111, v111, v184
	v_cvt_pk_bf16_f32 v112, v112, v185
	v_cvt_pk_bf16_f32 v113, v113, v186
	v_cvt_pk_bf16_f32 v114, v114, v187
	v_cvt_pk_bf16_f32 v115, v115, v188
	v_cvt_pk_bf16_f32 v116, v116, v189
	v_cvt_pk_bf16_f32 v117, v117, v190
	v_cvt_pk_bf16_f32 v118, v118, v191
	v_cvt_pk_bf16_f32 v119, v119, v192
	v_cvt_pk_bf16_f32 v120, v120, v193
	v_cvt_pk_bf16_f32 v121, v121, v194
	v_cmp_eq_u32_e32 vcc, 0, v205
	s_and_saveexec_b64 s[12:13], vcc
	ds_write_b32 v200, v82 offset:0
	ds_write_b32 v200, v83 offset:64
	ds_write_b32 v200, v84 offset:128
	ds_write_b32 v200, v85 offset:192
	ds_write_b32 v200, v86 offset:256
	ds_write_b32 v200, v87 offset:320
	ds_write_b32 v200, v88 offset:384
	ds_write_b32 v200, v89 offset:448
	ds_write_b32 v200, v90 offset:512
	ds_write_b32 v200, v91 offset:576
	ds_write_b32 v200, v92 offset:640
	ds_write_b32 v200, v93 offset:704
	ds_write_b32 v200, v94 offset:768
	ds_write_b32 v200, v95 offset:832
	ds_write_b32 v200, v96 offset:896
	ds_write_b32 v200, v97 offset:960
	ds_write_b32 v200, v106 offset:2048
	ds_write_b32 v200, v107 offset:2112
	ds_write_b32 v200, v108 offset:2176
	ds_write_b32 v200, v109 offset:2240
	ds_write_b32 v200, v110 offset:2304
	ds_write_b32 v200, v111 offset:2368
	ds_write_b32 v200, v112 offset:2432
	ds_write_b32 v200, v113 offset:2496
	ds_write_b32 v200, v114 offset:2560
	ds_write_b32 v200, v115 offset:2624
	ds_write_b32 v200, v116 offset:2688
	ds_write_b32 v200, v117 offset:2752
	ds_write_b32 v200, v118 offset:2816
	ds_write_b32 v200, v119 offset:2880
	ds_write_b32 v200, v120 offset:2944
	ds_write_b32 v200, v121 offset:3008
	s_or_b64 exec, exec, s[12:13]
	s_waitcnt lgkmcnt(0)
	ds_read_b128 v[122:125], v201 offset:0
	ds_read_b128 v[126:129], v201 offset:1024
	ds_read_b128 v[164:167], v201 offset:2048
	ds_read_b128 v[168:171], v201 offset:3072
	s_waitcnt lgkmcnt(0)
	v_add_u32_e32 v204, 0x58000, v203
	global_store_dwordx4 v204, v[122:125], s[0:1]
	v_add_u32_e32 v204, 0x6e000, v203
	global_store_dwordx4 v204, v[126:129], s[0:1]
	v_add_u32_e32 v204, 0x84000, v203
	global_store_dwordx4 v204, v[164:167], s[0:1]
	v_add_u32_e32 v204, 0x9a000, v203
	global_store_dwordx4 v204, v[168:171], s[0:1]
